# P3: workgroups of XCDs 4..7 run their dattn units before their ssd_states units (XCDs 0..3 keep the order) so the two kinds of memory load overlap
# speedup vs baseline: 1.0090x; 1.0036x over previous
.LBB0_1376:
	s_mov_b32 s100, 0
	v_readlane_b32 s12, v244, 47
	s_cmp_lt_i32 s12, 4
	s_cselect_b64 s[2:3], -1, 0
	s_and_b64 s[0:1], s[2:3], s[0:1]
	v_readlane_b32 s13, v244, 48
	v_readlane_b32 s14, v244, 49
	v_readlane_b32 s15, v244, 50
	v_writelane_b32 v244, s0, 52
	s_andn2_b64 vcc, exec, s[0:1]
	s_nop 0
	v_writelane_b32 v244, s1, 53
	v_writelane_b32 v244, s86, 54
	s_cbranch_vccnz .LBB0_1416
	s_bitcmp1_b32 s69, 7
	s_cbranch_scc0 .Lp3_ssd
	s_mov_b32 s100, 1
	s_branch .LBB0_1390
.Lp3_ssd:
	s_cmpk_gt_i32 s89, 0x2ff
	s_cbranch_scc1 .LBB0_1390
	v_lshlrev_b32_e32 v0, 5, v182
	v_mov_b32_e32 v35, 0
	v_readlane_b32 s12, v244, 0
	v_and_b32_e32 v32, 0x60, v0
	v_mov_b32_e32 v33, v35
	v_readlane_b32 s16, v244, 4
	v_readlane_b32 s17, v244, 5
	s_mov_b64 s[0:1], 0x6000000
	s_add_u32 s26, s16, 0x9000000
	v_lshl_add_u64 v[0:1], s[16:17], 0, v[32:33]
	v_lshl_add_u64 v[36:37], v[0:1], 0, s[0:1]
	v_mbcnt_lo_u32_b32 v0, -1, 0
	s_addc_u32 s27, s17, 0
	s_bfe_u32 s2, s87, 0x10006
	v_mbcnt_hi_u32_b32 v0, -1, v0
	v_readlane_b32 s18, v244, 6
	s_lshr_b32 s28, s87, 7
	s_lshl_b32 s29, s2, 3
	s_lshl_b32 s0, s2, 5
	v_and_b32_e32 v1, 64, v0
	v_add_u32_e32 v2, -1, v0
	v_readlane_b32 s19, v244, 7
	s_add_u32 s0, s18, s0
	v_cmp_lt_i32_e32 vcc, v2, v1
	s_addc_u32 s1, s19, 0
	s_add_u32 s30, s0, 0x1a000000
	v_cndmask_b32_e32 v2, v2, v0, vcc
	v_lshlrev_b32_e32 v105, 2, v2
	v_add_u32_e32 v2, -2, v0
	s_addc_u32 s31, s1, 0
	v_cmp_lt_i32_e64 s[0:1], v2, v1
	s_lshl_b32 s10, s88, 9
	s_add_i32 s39, s10, 0
	v_cndmask_b32_e64 v2, v2, v0, s[0:1]
	v_lshlrev_b32_e32 v106, 2, v2
	v_add_u32_e32 v2, -4, v0
	v_cmp_lt_i32_e64 s[4:5], v2, v1
	s_cmp_eq_u32 s2, 0
	s_cselect_b64 s[10:11], -1, 0
	v_cndmask_b32_e64 v2, v2, v0, s[4:5]
	v_lshlrev_b32_e32 v107, 2, v2
	v_add_u32_e32 v2, -8, v0
	v_cmp_lt_i32_e64 s[4:5], v2, v1
	s_add_u32 s18, s18, 0x1a400000
	s_addc_u32 s19, s19, 0
	v_cndmask_b32_e64 v2, v2, v0, s[4:5]
	v_lshlrev_b32_e32 v108, 2, v2
	v_add_u32_e32 v2, -16, v0
	v_cmp_lt_i32_e64 s[6:7], v2, v1
	s_lshl_b32 s20, s88, 1
	v_lshrrev_b32_e32 v10, 4, v144
	v_cndmask_b32_e64 v2, v2, v0, s[6:7]
	v_lshlrev_b32_e32 v109, 2, v2
	v_subrev_u32_e32 v2, 32, v0
	v_cmp_lt_i32_e64 s[8:9], v2, v1
	s_lshr_b32 s33, s87, 8
	s_and_b32 s20, s20, 6
	v_cndmask_b32_e64 v1, v2, v0, s[8:9]
	v_bfe_u32 v11, v182, 2, 2
	v_lshlrev_b32_e32 v110, 2, v1
	v_bfrev_b32_e32 v1, 0.5
	s_movk_i32 s16, 0x110
	s_cmpk_lt_u32 s87, 0x100
	s_mov_b32 s21, 0xac00
	v_lshlrev_b32_e32 v13, 9, v10
	v_lshl_or_b32 v10, v10, 3, v11
	v_lshl_or_b32 v111, v0, 2, v1
	v_and_b32_e32 v1, 15, v182
	s_cselect_b32 s21, s21, 0xf400
	v_mad_u32_u24 v117, v10, s16, 0
	s_or_b32 s16, s20, 1
	v_lshlrev_b32_e32 v0, 3, v1
	v_lshl_add_u32 v3, v1, 4, 0
	v_lshrrev_b32_e32 v4, 4, v182
	s_add_i32 s21, s21, 0
	v_lshl_or_b32 v21, s20, 4, v1
	v_lshl_or_b32 v1, s16, 4, v1
	v_or_b32_e32 v23, 0x880, v13
	v_or_b32_e32 v25, 0x900, v13
	v_or_b32_e32 v27, 0x980, v13
	v_lshlrev_b32_e32 v2, 9, v4
	v_mul_u32_u24_e32 v5, 0x110, v4
	v_add_u32_e32 v4, 0x200, v182
	v_add_u32_e32 v8, 0x600, v182
	s_movk_i32 s17, 0x90
	v_lshlrev_b32_e32 v12, 3, v182
	v_mov_b32_e32 v11, s21
	v_or_b32_e32 v16, v21, v23
	v_or_b32_e32 v18, v21, v25
	v_or_b32_e32 v20, v21, v27
	v_or_b32_e32 v24, v1, v23
	v_or_b32_e32 v26, v1, v25
	v_or_b32_e32 v28, v1, v27
	v_or_b32_e32 v23, 0x1000, v13
	v_or_b32_e32 v25, 0x1080, v13
	v_or_b32_e32 v27, 0x1100, v13
	v_lshrrev_b32_e32 v104, 2, v182
	v_lshrrev_b32_e32 v6, 4, v4
	v_lshrrev_b32_e32 v9, 4, v8
	v_and_b32_e32 v115, 24, v12
	v_mad_u32_u24 v116, v10, s17, v11
	v_or_b32_e32 v10, v21, v13
	v_or_b32_e32 v12, v1, v13
	v_or_b32_e32 v22, 0x800, v13
	v_or_b32_e32 v30, v21, v23
	v_or_b32_e32 v68, v21, v25
	v_or_b32_e32 v70, v21, v27
	v_or_b32_e32 v29, 0x1180, v13
	v_or_b32_e32 v74, v1, v23
	v_or_b32_e32 v76, v1, v25
	v_or_b32_e32 v78, v1, v27
	v_or_b32_e32 v23, 0x1800, v13
	v_or_b32_e32 v25, 0x1880, v13
	v_or_b32_e32 v27, 0x1900, v13
	v_or_b32_e32 v13, 0x1980, v13
	v_readlane_b32 s13, v244, 1
	v_readlane_b32 s14, v244, 2
	v_readlane_b32 s15, v244, 3
	s_mul_i32 s2, s88, 0xfffffe04
	v_lshlrev_b32_e32 v4, 9, v6
	v_mul_u32_u24_e32 v7, 0x110, v6
	v_or_b32_e32 v6, 0x8000, v2
	v_lshlrev_b32_e32 v8, 9, v9
	v_mul_u32_u24_e32 v9, 0x110, v9
	v_mad_u32_u24 v114, v104, s17, 0
	v_mul_i32_i24_e32 v15, 0xffffff74, v104
	v_add_u32_e32 v11, 0x1200, v116
	v_add_u32_e32 v17, 0x2400, v116
	v_add_u32_e32 v19, 0x3600, v116
	v_or_b32_e32 v14, v21, v22
	v_or_b32_e32 v22, v1, v22
	v_or_b32_e32 v72, v21, v29
	v_or_b32_e32 v80, v1, v29
	v_or_b32_e32 v82, v21, v23
	v_or_b32_e32 v84, v21, v25
	v_or_b32_e32 v86, v21, v27
	v_or_b32_e32 v88, v21, v13
	v_or_b32_e32 v90, v1, v23
	v_or_b32_e32 v92, v1, v25
	v_or_b32_e32 v94, v1, v27
	v_or_b32_e32 v96, v1, v13
	v_and_b32_e32 v1, 0x3fc, v182
	s_mov_b32 s3, 0
	v_lshlrev_b32_e32 v33, 1, v144
	v_cmp_eq_u32_e32 vcc, 0, v144
	v_cmp_gt_u32_e64 s[0:1], 2, v144
	v_cmp_gt_u32_e64 s[14:15], 4, v144
	v_cmp_gt_u32_e64 s[4:5], 8, v144
	v_cmp_gt_u32_e64 s[6:7], 16, v144
	v_cmp_gt_u32_e64 s[8:9], 32, v144
	v_lshl_add_u32 v112, v144, 3, s39
	v_cmp_lt_u32_e64 s[12:13], 7, v182
	v_lshl_add_u32 v113, v182, 2, 0
	v_lshl_or_b32 v118, s20, 5, v115
	v_lshl_or_b32 v119, s16, 5, v115
	v_add_u32_e32 v120, 0x2200, v117
	v_add_u32_e32 v121, 0x4400, v117
	v_add_u32_e32 v122, 0x6600, v117
	v_add_u32_e32 v123, 0, v1
	s_mov_b32 s34, 0x41a00000
	s_mov_b32 s35, 0x3f2aaaab
	v_mov_b32_e32 v124, 0x3ecc95a3
	s_mov_b32 s36, 0x3f317218
	s_mov_b32 s37, 0x7f800000
	s_mov_b32 s38, 0x33800000
	s_add_i32 s39, s39, s2
	v_lshlrev_b32_e32 v34, 1, v0
	v_lshlrev_b32_e32 v38, 1, v2
	v_add_u32_e32 v125, v3, v5
	v_lshlrev_b32_e32 v40, 1, v4
	v_add_u32_e32 v126, v3, v7
	v_lshlrev_b32_e32 v42, 1, v6
	v_lshlrev_b32_e32 v44, 1, v8
	v_add_u32_e32 v127, v3, v9
	v_add_u32_e32 v128, v114, v15
	v_add_u32_e32 v129, v11, v115
	v_add_u32_e32 v130, v17, v115
	v_add_u32_e32 v131, v19, v115
	v_lshlrev_b32_e32 v46, 1, v10
	v_lshlrev_b32_e32 v48, 1, v12
	v_lshlrev_b32_e32 v50, 1, v14
	v_lshlrev_b32_e32 v52, 1, v16
	v_lshlrev_b32_e32 v54, 1, v18
	v_lshlrev_b32_e32 v56, 1, v20
	v_lshlrev_b32_e32 v58, 1, v22
	v_lshlrev_b32_e32 v60, 1, v24
	v_lshlrev_b32_e32 v62, 1, v26
	v_lshlrev_b32_e32 v64, 1, v28
	v_lshlrev_b32_e32 v66, 1, v30
	v_lshlrev_b32_e32 v68, 1, v68
	v_lshlrev_b32_e32 v70, 1, v70
	v_lshlrev_b32_e32 v72, 1, v72
	v_lshlrev_b32_e32 v74, 1, v74
	v_lshlrev_b32_e32 v76, 1, v76
	v_lshlrev_b32_e32 v78, 1, v78
	v_lshlrev_b32_e32 v80, 1, v80
	v_lshlrev_b32_e32 v82, 1, v82
	v_lshlrev_b32_e32 v84, 1, v84
	v_lshlrev_b32_e32 v86, 1, v86
	v_lshlrev_b32_e32 v88, 1, v88
	v_lshlrev_b32_e32 v90, 1, v90
	v_lshlrev_b32_e32 v92, 1, v92
	v_lshlrev_b32_e32 v94, 1, v94
	v_lshlrev_b32_e32 v96, 1, v96
	v_mov_b32_e32 v98, 0x3f317218
	v_mov_b32_e32 v132, 0x7f800000
	v_mov_b32_e32 v133, 0x7fc00000
	v_mov_b32_e32 v134, 0xff800000
	s_mov_b32 s40, s89
	s_branch .LBB0_1380

.LBB0_1390:
	s_cmp_eq_u32 s100, 2
	s_cbranch_scc1 .LBB0_1415
	v_readlane_b32 s12, v244, 47
	v_readlane_b32 s14, v244, 49
	s_bitcmp0_b32 s14, 0
	s_cselect_b64 s[0:1], -1, 0
	s_cmpk_lt_i32 s69, 0x600
	s_cselect_b64 s[2:3], -1, 0
	s_and_b64 s[0:1], s[0:1], s[2:3]
	v_readlane_b32 s13, v244, 48
	s_andn2_b64 vcc, exec, s[0:1]
	v_readlane_b32 s15, v244, 50
	s_cbranch_vccnz .LBB0_1416
	v_mbcnt_lo_u32_b32 v0, -1, 0
	v_mbcnt_hi_u32_b32 v0, -1, v0
	v_and_b32_e32 v1, 64, v0
	v_add_u32_e32 v1, 64, v1
	v_xor_b32_e32 v2, 1, v0
	v_cmp_lt_i32_e32 vcc, v2, v1
	v_writelane_b32 v244, s89, 55
	s_movk_i32 s0, 0x1ff
	v_cndmask_b32_e32 v2, v0, v2, vcc
	v_lshlrev_b32_e32 v81, 2, v2
	v_xor_b32_e32 v2, 2, v0
	v_cmp_lt_i32_e32 vcc, v2, v1
	v_readlane_b32 s4, v244, 0
	v_readlane_b32 s10, v244, 6
	v_cndmask_b32_e32 v2, v0, v2, vcc
	v_lshlrev_b32_e32 v85, 2, v2
	v_xor_b32_e32 v2, 4, v0
	v_cmp_lt_i32_e32 vcc, v2, v1
	v_readlane_b32 s11, v244, 7
	s_add_u32 s90, s10, 0xf000000
	v_cndmask_b32_e32 v2, v0, v2, vcc
	v_lshlrev_b32_e32 v86, 2, v2
	v_xor_b32_e32 v2, 8, v0
	v_cmp_lt_i32_e32 vcc, v2, v1
	s_addc_u32 s91, s11, 0
	s_add_u32 s92, s10, 0x12000000
	v_cndmask_b32_e32 v2, v0, v2, vcc
	v_lshlrev_b32_e32 v87, 2, v2
	v_xor_b32_e32 v2, 16, v0
	v_cmp_lt_i32_e32 vcc, v2, v1
	s_addc_u32 s93, s11, 0
	s_add_u32 s94, s10, 0x15000000
	v_cndmask_b32_e32 v2, v0, v2, vcc
	v_lshlrev_b32_e32 v88, 2, v2
	v_xor_b32_e32 v2, 32, v0
	v_cmp_lt_i32_e32 vcc, v2, v1
	v_readlane_b32 s9, v244, 5
	s_addc_u32 s95, s11, 0
	v_cndmask_b32_e32 v0, v0, v2, vcc
	v_lshlrev_b32_e32 v89, 2, v0
	v_lshlrev_b32_e32 v0, 4, v182
	v_and_b32_e32 v90, 0x70, v0
	v_add_u32_e32 v0, 0x200, v182
	v_lshrrev_b32_e32 v92, 3, v0
	v_add_u32_e32 v0, 0x600, v182
	v_cmp_lt_u32_e32 vcc, s0, v182
	s_lshl_b32 s0, s88, 4
	v_readlane_b32 s8, v244, 4
	v_lshrrev_b32_e32 v94, 3, v0
	v_add_u32_e32 v0, 0xa00, v182
	v_mov_b32_e32 v2, 0xfffffe80
	s_and_b32 s9, s0, 48
	v_or_b32_e32 v9, 0x400, v182
	s_movk_i32 s0, 0x5ff
	v_and_b32_e32 v73, 15, v182
	s_lshl_b32 s8, s88, 5
	v_lshrrev_b32_e32 v1, 3, v0
	v_cndmask_b32_e64 v96, 0, 1, vcc
	v_cndmask_b32_e32 v2, 0, v2, vcc
	v_lshrrev_b32_e32 v10, 3, v9
	v_cmp_lt_u32_e32 vcc, s0, v9
	v_mov_b32_e32 v9, 0xffffff40
	v_mul_u32_u24_e32 v0, 0xaab, v0
	v_readlane_b32 s6, v244, 2
	v_cndmask_b32_e32 v9, 0, v9, vcc
	v_lshrrev_b32_e32 v105, 22, v0
	v_or_b32_e32 v0, s8, v73
	s_movk_i32 s1, 0x110
	s_add_i32 s4, 0, 0x11000
	s_mul_i32 s2, s88, 0x1200
	s_lshr_b32 s6, s87, 8
	s_movk_i32 s0, 0xff40
	v_add_u32_e32 v104, v9, v10
	v_mul_u32_u24_e32 v9, 0x90, v10
	v_mul_lo_u32 v10, v0, s1
	v_lshl_add_u32 v107, v0, 2, s4
	v_or_b32_e32 v0, s9, v73
	v_readlane_b32 s7, v244, 3
	v_lshrrev_b32_e32 v91, 3, v182
	v_add_u32_e32 v97, v2, v1
	v_add_u32_e32 v2, 0, v90
	s_movk_i32 s96, 0x90
	v_mad_i32_i24 v106, v105, s0, v1
	s_add_i32 s0, s2, 0
	v_lshl_add_u32 v0, v0, 2, s6
	s_lshl_b32 s7, s88, 1
	v_mad_u32_u24 v4, v91, s96, v2
	v_mul_u32_u24_e32 v7, 0x90, v1
	s_add_i32 s0, s0, 0x11400
	v_mul_lo_u32 v1, v0, s1
	v_lshl_add_u32 v110, v0, 2, s4
	v_lshrrev_b32_e32 v0, 3, v144
	v_readlane_b32 s16, v244, 15
	v_add_u32_e32 v98, 0x12000, v4
	v_add_u32_e32 v99, 0x16800, v4
	v_lshrrev_b32_e32 v4, 2, v144
	s_or_b32 s12, s7, 1
	v_add_u32_e32 v109, 0, v1
	v_or_b32_e32 v112, 0xffffffc0, v0
	v_mov_b32_e32 v1, s0
	v_mul_u32_u24_e32 v14, 0x90, v0
	v_lshlrev_b32_e32 v0, 4, v73
	v_readlane_b32 s17, v244, 16
	v_mad_u32_u24 v13, v4, s96, v1
	v_add_u32_e32 v1, s7, v0
	v_add_u32_e32 v0, s12, v0
	v_lshrrev_b32_e32 v123, 1, v182
	v_and_b32_e32 v17, 1, v182
	v_readlane_b32 s5, v244, 1
	v_lshlrev_b32_e32 v74, 2, v144
	v_mov_b32_e32 v75, 0
	v_readlane_b32 s18, v244, 17
	v_readlane_b32 s19, v244, 18
	v_readlane_b32 s20, v244, 19
	v_readlane_b32 s21, v244, 20
	v_readlane_b32 s22, v244, 21
	v_readlane_b32 s23, v244, 22
	v_readlane_b32 s24, v244, 23
	v_readlane_b32 s25, v244, 24
	v_readlane_b32 s26, v244, 25
	v_readlane_b32 s27, v244, 26
	v_readlane_b32 s28, v244, 27
	v_readlane_b32 s29, v244, 28
	v_readlane_b32 s30, v244, 29
	v_readlane_b32 s31, v244, 30
	v_writelane_b32 v244, s88, 56
	v_cmp_lt_u32_e64 s[16:17], 15, v144
	v_add_u32_e32 v12, s0, v90
	v_mul_lo_u32 v15, v1, s1
	v_mul_lo_u32 v16, v0, s1
	v_mad_u32_u24 v18, v123, s1, 0
	v_cmp_eq_u32_e64 s[0:1], 0, v17
	v_lshl_add_u64 v[76:77], s[24:25], 0, v[74:75]
	v_lshl_add_u64 v[78:79], s[26:27], 0, v[74:75]
	v_writelane_b32 v244, s16, 57
	s_bitcmp0_b32 s14, 1
	v_lshlrev_b32_e32 v74, 2, v123
	v_writelane_b32 v243, s0, 1
	v_and_b32_e32 v101, 12, v4
	v_writelane_b32 v244, s17, 58
	s_cselect_b64 s[14:15], -1, 0
	v_lshl_add_u32 v121, v1, 2, s4
	v_lshl_add_u32 v122, v0, 2, s4
	v_writelane_b32 v243, s1, 2
	v_lshl_add_u64 v[0:1], s[10:11], 0, v[74:75]
	s_mov_b64 s[0:1], 0x1fb50000
	v_writelane_b32 v244, s14, 59
	v_lshl_add_u64 v[82:83], v[0:1], 0, s[0:1]
	v_or_b32_e32 v1, s8, v101
	v_lshlrev_b32_e32 v8, 3, v182
	v_writelane_b32 v244, s15, 60
	v_writelane_b32 v243, s8, 3
	v_subrev_u32_e32 v125, 64, v1
	v_mov_b32_e32 v1, s2
	v_and_b32_e32 v8, 24, v8
	s_mul_i32 s3, s6, 0xc0
	v_writelane_b32 v244, s7, 61
	v_lshlrev_b32_e32 v19, 7, v17
	v_lshlrev_b32_e32 v0, 5, v17
	v_mad_u32_u24 v17, v73, s96, v1
	v_mad_u32_u24 v1, v4, s96, v1
	v_writelane_b32 v243, s87, 5
	s_bfe_u32 s7, s87, 0x20006
	s_mul_i32 s0, s6, 0x6c00
	s_mov_b32 s5, s69
	v_and_b32_e32 v100, 48, v182
	v_add3_u32 v127, v1, v8, 0
	s_mulk_i32 s7, 0x900
	v_mov_b32_e32 v1, s0
	v_writelane_b32 v243, s9, 7
	s_or_b32 s0, s3, s9
	v_mul_u32_u24_e32 v3, 0x90, v91
	v_mul_u32_u24_e32 v5, 0x90, v92
	v_mul_u32_u24_e32 v6, 0x90, v94
	v_add_u32_e32 v80, 0, v100
	v_cmp_gt_u32_e64 s[40:41], 16, v144
	v_add_u32_e32 v11, 0x220, v109
	v_add3_u32 v126, v17, v100, 0
	v_mad_u32_u24 v17, v4, s96, v1
	v_or_b32_e32 v4, s0, v4
	v_or_b32_e32 v131, s0, v73
	s_add_i32 s0, s7, 0
	v_writelane_b32 v243, s5, 9
	v_or_b32_e32 v93, 0x80, v91
	v_or_b32_e32 v95, 0x100, v91
	v_or_b32_e32 v72, 16, v73
	v_or_b32_e32 v102, 0xffffffc0, v101
	v_cndmask_b32_e64 v103, 0, 1, vcc
	v_add_u32_e32 v108, 64, v107
	v_add_u32_e32 v111, 8, v110
	v_or_b32_e32 v113, 0xffffffc0, v73
	v_or_b32_e32 v114, 0xffffffd0, v73
	v_or_b32_e32 v115, 0xffffffe0, v73
	v_or_b32_e32 v116, -16, v182
	v_or_b32_e32 v117, 32, v73
	v_or_b32_e32 v118, 48, v144
	v_or_b32_e32 v119, 64, v73
	v_or_b32_e32 v120, 0x50, v73
	v_add_u32_e32 v124, s4, v74
	v_add_u32_e32 v84, 0, v8
	v_or_b32_e32 v128, s9, v101
	v_add3_u32 v129, v17, v8, 0
	v_add_u32_e32 v130, 0x180, v4
	v_add_u32_e32 v132, s0, v100
	v_mad_u32_u24 v133, v73, s96, v1
	s_mov_b32 s4, 0x3e38aa3b
	s_movk_i32 s39, 0xbf
	v_add_u32_e32 v134, v11, v100
	v_add_u32_e32 v135, v80, v15
	v_add_u32_e32 v136, v80, v16
	v_add_u32_e32 v137, v18, v19
	v_lshlrev_b32_e32 v74, 1, v0
	v_add_u32_e32 v138, v2, v3
	v_add_u32_e32 v139, v2, v5
	v_add_u32_e32 v140, v2, v6
	v_add_u32_e32 v141, v2, v7
	v_add_u32_e32 v142, v2, v9
	v_add_u32_e32 v143, v80, v10
	v_add_u32_e32 v146, v12, v14
	v_add_u32_e32 v147, v13, v8
	v_writelane_b32 v243, s40, 10
	v_writelane_b32 v244, s12, 63
	s_nop 0
	v_writelane_b32 v243, s41, 11
	s_branch .LBB0_1393

.LBB0_1416:
	s_cmp_eq_u32 s100, 1
	s_cbranch_scc0 .Lp3_go
	s_mov_b32 s100, 2
	s_branch .Lp3_ssd
